# attention unit output stores: row halves paired across the half-waves with v_permlane32_swap into four dwordx4 stores instead of eight dwordx2
# baseline (speedup 1.0000x reference)
.LBB0_936:
	s_or_b64 exec, exec, s[2:3]
	s_waitcnt lgkmcnt(0)
	s_barrier
	s_and_saveexec_b64 s[2:3], s[6:7]
	s_cbranch_execz .LBB0_939
	v_lshlrev_b64 v[48:49], 11, v[0:1]
	v_lshl_add_u64 v[48:49], s[8:9], 0, v[48:49]
	s_lshl_b32 s10, s35, 7
	v_lshl_add_u64 v[56:57], v[48:49], 0, s[10:11]
	s_lshl_b32 s10, s35, 8
	v_lshl_add_u64 v[58:59], v[162:163], 0, s[10:11]
	ds_read2_b32 v[42:43], v204 offset1:1
	ds_read2_b32 v[40:41], v204 offset0:2 offset1:3
	ds_read2_b32 v[44:45], v204 offset0:4 offset1:5
	ds_read2_b32 v[46:47], v204 offset0:6 offset1:7
	global_load_dwordx4 v[48:51], v[58:59], off
	global_load_dwordx4 v[52:55], v[58:59], off offset:128
	global_load_dwordx4 v[108:111], v[58:59], off offset:32
	global_load_dwordx4 v[112:115], v[58:59], off offset:160
	global_load_dwordx4 v[116:119], v[58:59], off offset:64
	global_load_dwordx4 v[120:123], v[58:59], off offset:192
	global_load_dwordx4 v[124:127], v[58:59], off offset:96
	global_load_dwordx4 v[128:131], v[58:59], off offset:224
	v_max_f32_e32 v34, v95, v95
	s_waitcnt lgkmcnt(3)
	v_max_f32_e32 v35, v42, v42
	v_max_f32_e32 v35, v34, v35
	v_sub_f32_e32 v34, v95, v35
	v_sub_f32_e32 v35, v42, v35
	v_exp_f32_e32 v34, v34
	v_exp_f32_e32 v37, v35
	s_waitcnt lgkmcnt(1)
	v_mov_b32_e32 v35, v44
	v_mov_b32_e32 v36, v20
	v_mov_b32_e32 v42, v34
	v_mov_b32_e32 v39, v37
	v_pk_mul_f32 v[38:39], v[38:39], v[42:43]
	v_pk_mul_f32 v[60:61], v[36:37], v[34:35]
	v_add_f32_e32 v20, v38, v39
	v_div_scale_f32 v36, s[48:49], v20, v20, 1.0
	v_rcp_f32_e32 v42, v36
	v_mov_b32_e32 v35, v45
	v_add_f32_e32 v44, v60, v61
	ds_read2_b32 v[38:39], v204 offset0:20 offset1:21
	v_fma_f32 v43, -v36, v42, 1.0
	v_fmac_f32_e32 v42, v43, v42
	v_div_scale_f32 v43, vcc, 1.0, v20, 1.0
	v_mul_f32_e32 v45, v43, v42
	v_fma_f32 v60, -v36, v45, v43
	v_fmac_f32_e32 v45, v60, v42
	v_fma_f32 v36, -v36, v45, v43
	v_div_fmas_f32 v36, v36, v42, v45
	v_div_fixup_f32 v76, v36, v20, 1.0
	v_mov_b32_e32 v42, v34
	v_mov_b32_e32 v43, v40
	v_mov_b32_e32 v36, v18
	v_pk_mul_f32 v[42:43], v[36:37], v[42:43]
	v_mov_b32_e32 v40, v34
	v_add_f32_e32 v18, v42, v43
	v_mov_b32_e32 v36, v19
	v_mul_f32_e32 v77, v18, v76
	v_pk_mul_f32 v[18:19], v[36:37], v[40:41]
	ds_read2_b32 v[40:41], v204 offset0:18 offset1:19
	ds_read2_b32 v[42:43], v204 offset0:22 offset1:23
	v_add_f32_e32 v18, v18, v19
	v_mul_f32_e32 v78, v76, v18
	v_mov_b32_e32 v18, v34
	s_waitcnt lgkmcnt(2)
	v_mov_b32_e32 v19, v38
	v_mov_b32_e32 v36, v4
	v_pk_mul_f32 v[18:19], v[36:37], v[18:19]
	v_mov_b32_e32 v36, v21
	v_add_f32_e32 v4, v18, v19
	v_pk_mul_f32 v[18:19], v[36:37], v[34:35]
	v_mul_f32_e32 v80, v76, v4
	v_add_f32_e32 v4, v18, v19
	v_mov_b32_e32 v18, v34
	s_waitcnt lgkmcnt(1)
	v_mov_b32_e32 v19, v40
	v_mov_b32_e32 v36, v2
	v_pk_mul_f32 v[18:19], v[36:37], v[18:19]
	v_mov_b32_e32 v40, v34
	v_add_f32_e32 v2, v18, v19
	v_mov_b32_e32 v36, v3
	v_mul_f32_e32 v82, v2, v76
	v_pk_mul_f32 v[2:3], v[36:37], v[40:41]
	v_mov_b32_e32 v35, v39
	v_add_f32_e32 v2, v2, v3
	v_mov_b32_e32 v36, v5
	v_mul_f32_e32 v83, v76, v2
	v_pk_mul_f32 v[2:3], v[36:37], v[34:35]
	v_mul_f32_e32 v79, v76, v44
	v_add_f32_e32 v2, v2, v3
	v_mul_f32_e32 v81, v76, v4
	ds_read2_b32 v[44:45], v204 offset0:16 offset1:17
	v_mul_f32_e32 v84, v76, v2
	ds_read2_b32 v[4:5], v204 offset0:8 offset1:9
	ds_read2_b32 v[60:61], v204 offset0:10 offset1:11
	ds_read2_b32 v[62:63], v204 offset0:12 offset1:13
	ds_read2_b32 v[64:65], v204 offset0:14 offset1:15
	ds_read2_b32 v[66:67], v204 offset0:24 offset1:25
	ds_read2_b32 v[68:69], v204 offset0:26 offset1:27
	ds_read2_b32 v[70:71], v204 offset0:28 offset1:29
	ds_read2_b32 v[72:73], v204 offset0:30 offset1:31
	ds_read2_b32 v[74:75], v204 offset0:32 offset1:33
	v_lshlrev_b32_e32 v2, 1, v197
	v_mov_b32_e32 v3, v1
	v_lshl_add_u64 v[2:3], v[56:57], 0, v[2:3]
	v_and_b32_e32 v140, 32, v214
	v_lshrrev_b32_e32 v140, 2, v140
	v_mov_b32_e32 v141, 0
	v_lshl_add_u64 v[140:141], v[2:3], 0, v[140:141]
	s_waitcnt lgkmcnt(8)
	v_mov_b32_e32 v35, v4
	v_mov_b32_e32 v36, v24
	v_mul_f32_e32 v56, v83, v83
	v_fmac_f32_e32 v56, v78, v78
	s_waitcnt vmcnt(0)
	v_mul_f32_e32 v18, v77, v48
	v_mul_f32_e32 v19, v78, v49
	v_cvt_pk_bf16_f32 v18, v18, v19
	v_mul_f32_e32 v19, v79, v50
	v_mul_f32_e32 v20, v81, v51
	v_cvt_pk_bf16_f32 v19, v19, v20
	v_mov_b32_e32 v132, v18
	v_mov_b32_e32 v133, v19
	v_mul_f32_e32 v18, v82, v52
	v_mul_f32_e32 v19, v83, v53
	v_cvt_pk_bf16_f32 v18, v18, v19
	v_mul_f32_e32 v19, v80, v54
	v_mul_f32_e32 v20, v84, v55
	v_cvt_pk_bf16_f32 v19, v19, v20
	v_mov_b32_e32 v136, v18
	v_mov_b32_e32 v137, v19
	v_mov_b32_e32 v18, v108
	v_mov_b32_e32 v19, v109
	v_mov_b32_e32 v20, v110
	v_mov_b32_e32 v21, v111
	s_nop 0
	v_mov_b32_e32 v38, v112
	v_mov_b32_e32 v39, v113
	v_mov_b32_e32 v40, v114
	v_mov_b32_e32 v41, v115
	v_mov_b32_e32 v49, v46
	v_mov_b32_e32 v48, v34
	v_pk_mul_f32 v[54:55], v[36:37], v[34:35]
	v_mov_b32_e32 v36, v22
	v_mov_b32_e32 v46, v34
	v_mov_b32_e32 v35, v5
	v_pk_mul_f32 v[4:5], v[36:37], v[48:49]
	v_mov_b32_e32 v36, v23
	s_waitcnt lgkmcnt(4)
	v_mov_b32_e32 v51, v66
	v_mov_b32_e32 v50, v34
	v_add_f32_e32 v23, v4, v5
	v_pk_mul_f32 v[4:5], v[36:37], v[46:47]
	v_mov_b32_e32 v36, v8
	v_add_f32_e32 v8, v4, v5
	v_pk_mul_f32 v[4:5], v[36:37], v[50:51]
	v_mov_b32_e32 v36, v25
	v_mov_b32_e32 v53, v42
	v_mov_b32_e32 v52, v34
	v_add_f32_e32 v24, v4, v5
	v_pk_mul_f32 v[4:5], v[36:37], v[34:35]
	v_mov_b32_e32 v36, v6
	v_mov_b32_e32 v42, v34
	v_add_f32_e32 v6, v4, v5
	v_pk_mul_f32 v[4:5], v[36:37], v[52:53]
	v_mov_b32_e32 v36, v7
	v_mov_b32_e32 v35, v67
	v_add_f32_e32 v7, v4, v5
	v_pk_mul_f32 v[4:5], v[36:37], v[42:43]
	v_mov_b32_e32 v36, v9
	v_add_f32_e32 v9, v4, v5
	v_pk_mul_f32 v[4:5], v[36:37], v[34:35]
	v_add_f32_e32 v22, v54, v55
	v_mul_f32_e32 v49, v76, v23
	v_mul_f32_e32 v50, v76, v8
	v_add_f32_e32 v4, v4, v5
	v_mul_f32_e32 v48, v76, v22
	v_mul_f32_e32 v52, v76, v6
	v_mul_f32_e32 v55, v76, v4
	v_mul_f32_e32 v51, v76, v24
	v_mul_f32_e32 v53, v76, v7
	v_mul_f32_e32 v54, v76, v9
	v_mov_b32_e32 v35, v62
	v_mov_b32_e32 v36, v28
	v_pk_mul_f32 v[46:47], v[36:37], v[34:35]
	v_mov_b32_e32 v36, v26
	v_add_f32_e32 v46, v46, v47
	s_waitcnt lgkmcnt(2)
	v_mov_b32_e32 v23, v70
	v_mov_b32_e32 v22, v34
	v_mov_b32_e32 v35, v63
	v_mov_b32_e32 v25, v68
	v_mov_b32_e32 v24, v34
	v_mov_b32_e32 v68, v34
	v_mul_f32_e32 v28, v82, v82
	v_mul_f32_e32 v26, v80, v80
	v_fmac_f32_e32 v28, v77, v77
	v_mul_f32_e32 v57, v84, v84
	v_fmac_f32_e32 v26, v79, v79
	v_fmac_f32_e32 v57, v81, v81
	s_waitcnt lgkmcnt(1)
	v_mov_b32_e32 v43, v72
	v_mov_b32_e32 v72, v34
	v_mul_f32_e32 v4, v49, v18
	v_mul_f32_e32 v5, v50, v19
	v_mul_f32_e32 v6, v48, v20
	v_mul_f32_e32 v7, v52, v21
	v_cvt_pk_bf16_f32 v4, v4, v5
	v_cvt_pk_bf16_f32 v5, v6, v7
	v_mul_f32_e32 v8, v53, v38
	v_mul_f32_e32 v9, v54, v39
	v_mul_f32_e32 v18, v51, v40
	v_mul_f32_e32 v19, v55, v41
	v_mov_b32_e32 v134, v4
	v_mov_b32_e32 v135, v5
	s_nop 1
	v_permlane32_swap_b32_e32 v132, v134
	v_permlane32_swap_b32_e32 v133, v135
	global_store_dwordx4 v[140:141], v[132:135], off
	v_cvt_pk_bf16_f32 v4, v8, v9
	v_cvt_pk_bf16_f32 v5, v18, v19
	v_mov_b32_e32 v138, v4
	v_mov_b32_e32 v139, v5
	s_nop 1
	v_permlane32_swap_b32_e32 v136, v138
	v_permlane32_swap_b32_e32 v137, v139
	global_store_dwordx4 v[140:141], v[136:139], off offset:64
	v_mov_b32_e32 v4, v116
	v_mov_b32_e32 v5, v117
	v_mov_b32_e32 v6, v118
	v_mov_b32_e32 v7, v119
	s_nop 0
	v_mov_b32_e32 v18, v120
	v_mov_b32_e32 v19, v121
	v_mov_b32_e32 v20, v122
	v_mov_b32_e32 v21, v123
	v_mov_b32_e32 v9, v60
	v_mov_b32_e32 v8, v34
	v_mov_b32_e32 v60, v34
	v_pk_mul_f32 v[8:9], v[36:37], v[8:9]
	v_mov_b32_e32 v36, v27
	v_mul_f32_e32 v27, v76, v46
	v_add_f32_e32 v46, v8, v9
	v_pk_mul_f32 v[8:9], v[36:37], v[60:61]
	v_mov_b32_e32 v36, v12
	v_add_f32_e32 v12, v8, v9
	v_pk_mul_f32 v[8:9], v[36:37], v[22:23]
	v_mov_b32_e32 v36, v29
	v_mul_f32_e32 v22, v76, v12
	v_add_f32_e32 v12, v8, v9
	v_pk_mul_f32 v[8:9], v[36:37], v[34:35]
	v_mov_b32_e32 v36, v10
	v_add_f32_e32 v10, v8, v9
	v_pk_mul_f32 v[8:9], v[36:37], v[24:25]
	v_mov_b32_e32 v36, v11
	v_mov_b32_e32 v35, v71
	v_mul_f32_e32 v24, v76, v10
	v_add_f32_e32 v10, v8, v9
	v_pk_mul_f32 v[8:9], v[36:37], v[68:69]
	v_mov_b32_e32 v36, v13
	v_mul_f32_e32 v46, v76, v46
	v_mul_f32_e32 v25, v76, v10
	v_add_f32_e32 v10, v8, v9
	v_pk_mul_f32 v[8:9], v[36:37], v[34:35]
	v_mul_f32_e32 v23, v76, v12
	v_add_f32_e32 v8, v8, v9
	v_mul_f32_e32 v29, v76, v10
	v_mul_f32_e32 v47, v76, v8
	v_mul_f32_e32 v51, v51, v51
	v_fmac_f32_e32 v51, v48, v48
	v_mov_b32_e32 v35, v44
	v_mov_b32_e32 v36, v32
	v_mov_b32_e32 v39, v64
	v_mov_b32_e32 v38, v34
	v_mov_b32_e32 v64, v34
	s_waitcnt lgkmcnt(0)
	v_mov_b32_e32 v41, v74
	v_mov_b32_e32 v40, v34
	v_mul_f32_e32 v4, v46, v4
	v_mul_f32_e32 v5, v22, v5
	v_mul_f32_e32 v6, v27, v6
	v_mul_f32_e32 v7, v24, v7
	v_cvt_pk_bf16_f32 v4, v4, v5
	v_cvt_pk_bf16_f32 v5, v6, v7
	v_mul_f32_e32 v8, v25, v18
	v_mul_f32_e32 v9, v29, v19
	v_mul_f32_e32 v10, v23, v20
	v_mul_f32_e32 v11, v47, v21
	v_mov_b32_e32 v132, v4
	v_mov_b32_e32 v133, v5
	v_cvt_pk_bf16_f32 v4, v8, v9
	v_cvt_pk_bf16_f32 v5, v10, v11
	v_mov_b32_e32 v136, v4
	v_mov_b32_e32 v137, v5
	v_mov_b32_e32 v6, v124
	v_mov_b32_e32 v7, v125
	v_mov_b32_e32 v8, v126
	v_mov_b32_e32 v9, v127
	v_mov_b32_e32 v10, v128
	v_mov_b32_e32 v11, v129
	v_mov_b32_e32 v12, v130
	v_mov_b32_e32 v13, v131
	v_add_f32_e32 v19, v28, v56
	v_mul_f32_e32 v4, v53, v53
	v_add_f32_e32 v19, v19, v26
	v_mul_f32_e32 v5, v54, v54
	v_fmac_f32_e32 v4, v49, v49
	v_add_f32_e32 v19, v19, v57
	v_fmac_f32_e32 v5, v50, v50
	v_add_f32_e32 v4, v19, v4
	v_mul_f32_e32 v18, v55, v55
	v_add_f32_e32 v4, v4, v5
	v_fmac_f32_e32 v18, v52, v52
	v_add_f32_e32 v20, v4, v51
	v_mul_f32_e32 v21, v25, v25
	v_pk_mul_f32 v[4:5], v[36:37], v[34:35]
	v_mov_b32_e32 v36, v30
	v_mul_f32_e32 v19, v23, v23
	v_add_f32_e32 v18, v20, v18
	v_fmac_f32_e32 v21, v46, v46
	v_mul_f32_e32 v20, v29, v29
	v_add_f32_e32 v23, v4, v5
	v_pk_mul_f32 v[4:5], v[36:37], v[38:39]
	v_mov_b32_e32 v36, v31
	v_add_f32_e32 v18, v18, v21
	v_fmac_f32_e32 v20, v22, v22
	v_mul_f32_e32 v22, v76, v23
	v_add_f32_e32 v23, v4, v5
	v_pk_mul_f32 v[4:5], v[36:37], v[64:65]
	v_mov_b32_e32 v36, v16
	v_fmac_f32_e32 v19, v27, v27
	v_mov_b32_e32 v35, v45
	v_mul_f32_e32 v21, v47, v47
	v_add_f32_e32 v16, v18, v20
	v_add_f32_e32 v20, v4, v5
	v_pk_mul_f32 v[4:5], v[36:37], v[40:41]
	v_mov_b32_e32 v36, v33
	v_fmac_f32_e32 v21, v24, v24
	v_add_f32_e32 v16, v16, v19
	v_mul_f32_e32 v19, v76, v20
	v_add_f32_e32 v20, v4, v5
	v_pk_mul_f32 v[4:5], v[36:37], v[34:35]
	v_mov_b32_e32 v36, v14
	v_add_f32_e32 v14, v16, v21
	v_mul_f32_e32 v16, v76, v20
	v_add_f32_e32 v20, v4, v5
	v_pk_mul_f32 v[4:5], v[36:37], v[42:43]
	v_mov_b32_e32 v36, v15
	v_add_f32_e32 v21, v4, v5
	v_pk_mul_f32 v[4:5], v[36:37], v[72:73]
	v_mov_b32_e32 v35, v75
	v_mov_b32_e32 v36, v17
	v_mul_f32_e32 v17, v76, v21
	v_add_f32_e32 v21, v4, v5
	v_mul_f32_e32 v18, v76, v23
	v_pk_mul_f32 v[4:5], v[36:37], v[34:35]
	v_mul_f32_e32 v23, v17, v17
	v_mul_f32_e32 v21, v76, v21
	v_add_f32_e32 v4, v4, v5
	v_fmac_f32_e32 v23, v18, v18
	v_mul_f32_e32 v5, v21, v21
	v_mul_f32_e32 v15, v16, v16
	v_mul_f32_e32 v24, v76, v4
	v_add_f32_e32 v4, v14, v23
	v_fmac_f32_e32 v5, v19, v19
	v_mul_f32_e32 v20, v76, v20
	v_fmac_f32_e32 v15, v22, v22
	v_mul_f32_e32 v14, v24, v24
	v_add_f32_e32 v4, v4, v5
	v_fmac_f32_e32 v14, v20, v20
	v_add_f32_e32 v4, v4, v15
	v_add_f32_e32 v4, v4, v14
	ds_bpermute_b32 v5, v96, v4
	v_mul_f32_e32 v6, v18, v6
	v_mul_f32_e32 v7, v19, v7
	v_mul_f32_e32 v8, v22, v8
	v_mul_f32_e32 v9, v20, v9
	v_cvt_pk_bf16_f32 v6, v6, v7
	v_cvt_pk_bf16_f32 v7, v8, v9
	v_mul_f32_e32 v10, v17, v10
	v_mul_f32_e32 v11, v21, v11
	v_mul_f32_e32 v12, v16, v12
	v_mul_f32_e32 v13, v24, v13
	v_mov_b32_e32 v134, v6
	v_mov_b32_e32 v135, v7
	s_nop 1
	v_permlane32_swap_b32_e32 v132, v134
	v_permlane32_swap_b32_e32 v133, v135
	global_store_dwordx4 v[140:141], v[132:135], off offset:32
	v_cvt_pk_bf16_f32 v6, v10, v11
	v_cvt_pk_bf16_f32 v7, v12, v13
	v_mov_b32_e32 v138, v6
	v_mov_b32_e32 v139, v7
	s_nop 1
	v_permlane32_swap_b32_e32 v136, v138
	v_permlane32_swap_b32_e32 v137, v139
	global_store_dwordx4 v[140:141], v[136:139], off offset:96
	s_and_b64 exec, exec, s[0:1]
	s_cbranch_execz .LBB0_939
	v_lshlrev_b64 v[2:3], 5, v[0:1]
	v_lshl_add_u64 v[2:3], s[20:21], 0, v[2:3]
	s_lshl_b32 s10, s35, 2
	v_lshl_add_u64 v[2:3], v[2:3], 0, s[10:11]
	s_waitcnt lgkmcnt(0)
	v_add_f32_e32 v0, v4, v5
	global_store_dword v[2:3], v0, off

.LBB0_961:
	s_or_b64 exec, exec, s[2:3]
	s_waitcnt lgkmcnt(0)
	s_barrier
	s_and_saveexec_b64 s[2:3], s[6:7]
	s_cbranch_execz .LBB0_929
	v_lshlrev_b64 v[46:47], 11, v[178:179]
	v_lshl_add_u64 v[46:47], s[8:9], 0, v[46:47]
	s_lshl_b32 s10, s47, 7
	v_lshl_add_u64 v[56:57], v[46:47], 0, s[10:11]
	s_lshl_b32 s10, s47, 8
	v_lshl_add_u64 v[58:59], v[162:163], 0, s[10:11]
	ds_read2_b32 v[40:41], v204 offset1:1
	ds_read2_b32 v[38:39], v204 offset0:2 offset1:3
	ds_read2_b32 v[42:43], v204 offset0:4 offset1:5
	ds_read2_b32 v[44:45], v204 offset0:6 offset1:7
	global_load_dwordx4 v[48:51], v[58:59], off
	global_load_dwordx4 v[52:55], v[58:59], off offset:128
	global_load_dwordx4 v[108:111], v[58:59], off offset:32
	global_load_dwordx4 v[112:115], v[58:59], off offset:160
	global_load_dwordx4 v[116:119], v[58:59], off offset:64
	global_load_dwordx4 v[120:123], v[58:59], off offset:192
	global_load_dwordx4 v[124:127], v[58:59], off offset:96
	global_load_dwordx4 v[128:131], v[58:59], off offset:224
	v_max_f32_e32 v0, v173, v173
	s_waitcnt lgkmcnt(3)
	v_max_f32_e32 v34, v40, v40
	v_max_f32_e32 v0, v0, v34
	v_sub_f32_e32 v34, v173, v0
	v_sub_f32_e32 v0, v40, v0
	v_exp_f32_e32 v34, v34
	v_exp_f32_e32 v47, v0
	v_mov_b32_e32 v46, v20
	s_waitcnt lgkmcnt(1)
	v_mov_b32_e32 v35, v42
	v_mov_b32_e32 v40, v34
	v_mov_b32_e32 v37, v47
	v_pk_mul_f32 v[36:37], v[36:37], v[40:41]
	v_pk_mul_f32 v[60:61], v[46:47], v[34:35]
	v_add_f32_e32 v0, v36, v37
	v_div_scale_f32 v20, s[34:35], v0, v0, 1.0
	v_rcp_f32_e32 v40, v20
	v_mov_b32_e32 v35, v43
	ds_read2_b32 v[36:37], v204 offset0:20 offset1:21
	v_add_f32_e32 v42, v60, v61
	v_fma_f32 v41, -v20, v40, 1.0
	v_fmac_f32_e32 v40, v41, v40
	v_div_scale_f32 v41, vcc, 1.0, v0, 1.0
	v_mul_f32_e32 v43, v41, v40
	v_fma_f32 v46, -v20, v43, v41
	v_fmac_f32_e32 v43, v46, v40
	v_fma_f32 v20, -v20, v43, v41
	v_div_fmas_f32 v20, v20, v40, v43
	v_mov_b32_e32 v40, v34
	v_mov_b32_e32 v41, v38
	v_mov_b32_e32 v46, v18
	v_pk_mul_f32 v[40:41], v[46:47], v[40:41]
	v_mov_b32_e32 v38, v34
	v_mov_b32_e32 v46, v19
	v_div_fixup_f32 v76, v20, v0, 1.0
	v_add_f32_e32 v0, v40, v41
	v_pk_mul_f32 v[18:19], v[46:47], v[38:39]
	ds_read2_b32 v[38:39], v204 offset0:18 offset1:19
	ds_read2_b32 v[40:41], v204 offset0:22 offset1:23
	v_mul_f32_e32 v77, v0, v76
	v_add_f32_e32 v0, v18, v19
	v_mov_b32_e32 v18, v34
	s_waitcnt lgkmcnt(2)
	v_mov_b32_e32 v19, v36
	v_mov_b32_e32 v46, v4
	v_pk_mul_f32 v[18:19], v[46:47], v[18:19]
	v_mov_b32_e32 v46, v21
	v_mul_f32_e32 v78, v76, v0
	v_add_f32_e32 v0, v18, v19
	v_pk_mul_f32 v[18:19], v[46:47], v[34:35]
	v_mul_f32_e32 v80, v76, v0
	v_add_f32_e32 v0, v18, v19
	v_mov_b32_e32 v18, v34
	s_waitcnt lgkmcnt(1)
	v_mov_b32_e32 v19, v38
	v_mov_b32_e32 v46, v2
	v_pk_mul_f32 v[18:19], v[46:47], v[18:19]
	v_mov_b32_e32 v38, v34
	v_mov_b32_e32 v46, v3
	v_mul_f32_e32 v81, v76, v0
	v_mov_b32_e32 v35, v37
	v_add_f32_e32 v0, v18, v19
	v_pk_mul_f32 v[2:3], v[46:47], v[38:39]
	v_mov_b32_e32 v46, v5
	v_mul_f32_e32 v82, v0, v76
	v_add_f32_e32 v0, v2, v3
	v_pk_mul_f32 v[2:3], v[46:47], v[34:35]
	v_mul_f32_e32 v83, v76, v0
	v_add_f32_e32 v0, v2, v3
	v_mul_f32_e32 v84, v76, v0
	v_lshlrev_b32_e32 v0, 1, v197
	v_mul_f32_e32 v79, v76, v42
	v_lshl_add_u64 v[2:3], v[56:57], 0, v[0:1]
	v_and_b32_e32 v140, 32, v214
	v_lshrrev_b32_e32 v140, 2, v140
	v_mov_b32_e32 v141, 0
	v_lshl_add_u64 v[140:141], v[2:3], 0, v[140:141]
	ds_read2_b32 v[42:43], v204 offset0:16 offset1:17
	ds_read2_b32 v[4:5], v204 offset0:8 offset1:9
	ds_read2_b32 v[60:61], v204 offset0:10 offset1:11
	ds_read2_b32 v[62:63], v204 offset0:12 offset1:13
	ds_read2_b32 v[64:65], v204 offset0:14 offset1:15
	ds_read2_b32 v[66:67], v204 offset0:24 offset1:25
	ds_read2_b32 v[68:69], v204 offset0:26 offset1:27
	ds_read2_b32 v[70:71], v204 offset0:28 offset1:29
	ds_read2_b32 v[72:73], v204 offset0:30 offset1:31
	ds_read2_b32 v[74:75], v204 offset0:32 offset1:33
	s_waitcnt lgkmcnt(8)
	v_mov_b32_e32 v35, v4
	v_mov_b32_e32 v46, v24
	v_mov_b32_e32 v24, v34
	v_mul_f32_e32 v56, v84, v84
	v_fmac_f32_e32 v56, v81, v81
	s_waitcnt vmcnt(0)
	v_mul_f32_e32 v0, v77, v48
	v_mul_f32_e32 v18, v78, v49
	v_mul_f32_e32 v19, v81, v51
	v_cvt_pk_bf16_f32 v18, v0, v18
	v_mul_f32_e32 v0, v79, v50
	v_cvt_pk_bf16_f32 v19, v0, v19
	v_mov_b32_e32 v132, v18
	v_mov_b32_e32 v133, v19
	v_mul_f32_e32 v0, v82, v52
	v_mul_f32_e32 v18, v83, v53
	v_mul_f32_e32 v19, v84, v55
	v_cvt_pk_bf16_f32 v18, v0, v18
	v_mul_f32_e32 v0, v80, v54
	v_cvt_pk_bf16_f32 v19, v0, v19
	v_mov_b32_e32 v136, v18
	v_mov_b32_e32 v137, v19
	v_mov_b32_e32 v18, v108
	v_mov_b32_e32 v19, v109
	v_mov_b32_e32 v20, v110
	v_mov_b32_e32 v21, v111
	s_nop 0
	v_mov_b32_e32 v36, v112
	v_mov_b32_e32 v37, v113
	v_mov_b32_e32 v38, v114
	v_mov_b32_e32 v39, v115
	v_mov_b32_e32 v49, v44
	v_mov_b32_e32 v48, v34
	v_pk_mul_f32 v[54:55], v[46:47], v[34:35]
	v_mov_b32_e32 v46, v22
	v_mov_b32_e32 v44, v34
	v_mov_b32_e32 v35, v5
	v_pk_mul_f32 v[4:5], v[46:47], v[48:49]
	v_mov_b32_e32 v46, v23
	s_waitcnt lgkmcnt(4)
	v_mov_b32_e32 v51, v66
	v_mov_b32_e32 v50, v34
	v_add_f32_e32 v22, v4, v5
	v_pk_mul_f32 v[4:5], v[46:47], v[44:45]
	v_mov_b32_e32 v46, v8
	v_add_f32_e32 v8, v4, v5
	v_pk_mul_f32 v[4:5], v[46:47], v[50:51]
	v_mov_b32_e32 v46, v25
	v_mov_b32_e32 v53, v40
	v_mov_b32_e32 v52, v34
	v_add_f32_e32 v23, v4, v5
	v_pk_mul_f32 v[4:5], v[46:47], v[34:35]
	v_mov_b32_e32 v46, v6
	v_mov_b32_e32 v40, v34
	v_add_f32_e32 v6, v4, v5
	v_pk_mul_f32 v[4:5], v[46:47], v[52:53]
	v_mov_b32_e32 v46, v7
	v_mov_b32_e32 v35, v67
	v_add_f32_e32 v7, v4, v5
	v_pk_mul_f32 v[4:5], v[46:47], v[40:41]
	v_mov_b32_e32 v46, v9
	v_add_f32_e32 v9, v4, v5
	v_pk_mul_f32 v[4:5], v[46:47], v[34:35]
	v_add_f32_e32 v0, v54, v55
	v_mul_f32_e32 v48, v76, v22
	v_mul_f32_e32 v49, v76, v8
	v_add_f32_e32 v4, v4, v5
	v_mul_f32_e32 v0, v76, v0
	v_mul_f32_e32 v51, v76, v6
	v_mul_f32_e32 v54, v76, v4
	v_mul_f32_e32 v50, v76, v23
	v_mul_f32_e32 v52, v76, v7
	v_mul_f32_e32 v53, v76, v9
	v_mov_b32_e32 v35, v62
	v_mov_b32_e32 v46, v28
	v_pk_mul_f32 v[44:45], v[46:47], v[34:35]
	v_mov_b32_e32 v46, v26
	v_add_f32_e32 v44, v44, v45
	s_waitcnt lgkmcnt(2)
	v_mov_b32_e32 v23, v70
	v_mov_b32_e32 v22, v34
	v_mov_b32_e32 v35, v63
	v_mov_b32_e32 v25, v68
	v_mov_b32_e32 v68, v34
	v_mul_f32_e32 v28, v82, v82
	v_mul_f32_e32 v55, v83, v83
	v_mul_f32_e32 v26, v80, v80
	v_fmac_f32_e32 v28, v77, v77
	v_fmac_f32_e32 v55, v78, v78
	v_fmac_f32_e32 v26, v79, v79
	s_waitcnt lgkmcnt(1)
	v_mov_b32_e32 v41, v72
	v_mov_b32_e32 v72, v34
	v_mul_f32_e32 v4, v48, v18
	v_mul_f32_e32 v5, v49, v19
	v_mul_f32_e32 v6, v0, v20
	v_mul_f32_e32 v7, v51, v21
	v_cvt_pk_bf16_f32 v4, v4, v5
	v_cvt_pk_bf16_f32 v5, v6, v7
	v_mul_f32_e32 v8, v52, v36
	v_mul_f32_e32 v9, v53, v37
	v_mul_f32_e32 v18, v50, v38
	v_mul_f32_e32 v19, v54, v39
	v_mov_b32_e32 v134, v4
	v_mov_b32_e32 v135, v5
	s_nop 1
	v_permlane32_swap_b32_e32 v132, v134
	v_permlane32_swap_b32_e32 v133, v135
	global_store_dwordx4 v[140:141], v[132:135], off
	v_cvt_pk_bf16_f32 v4, v8, v9
	v_cvt_pk_bf16_f32 v5, v18, v19
	v_mov_b32_e32 v138, v4
	v_mov_b32_e32 v139, v5
	s_nop 1
	v_permlane32_swap_b32_e32 v136, v138
	v_permlane32_swap_b32_e32 v137, v139
	global_store_dwordx4 v[140:141], v[136:139], off offset:64
	v_mov_b32_e32 v4, v116
	v_mov_b32_e32 v5, v117
	v_mov_b32_e32 v6, v118
	v_mov_b32_e32 v7, v119
	s_nop 0
	v_mov_b32_e32 v18, v120
	v_mov_b32_e32 v19, v121
	v_mov_b32_e32 v20, v122
	v_mov_b32_e32 v21, v123
	v_mov_b32_e32 v9, v60
	v_mov_b32_e32 v8, v34
	v_mov_b32_e32 v60, v34
	v_pk_mul_f32 v[8:9], v[46:47], v[8:9]
	v_mov_b32_e32 v46, v27
	v_mul_f32_e32 v27, v76, v44
	v_add_f32_e32 v44, v8, v9
	v_pk_mul_f32 v[8:9], v[46:47], v[60:61]
	v_mov_b32_e32 v46, v12
	v_add_f32_e32 v12, v8, v9
	v_pk_mul_f32 v[8:9], v[46:47], v[22:23]
	v_mov_b32_e32 v46, v29
	v_mul_f32_e32 v22, v76, v12
	v_add_f32_e32 v12, v8, v9
	v_pk_mul_f32 v[8:9], v[46:47], v[34:35]
	v_mov_b32_e32 v46, v10
	v_add_f32_e32 v10, v8, v9
	v_pk_mul_f32 v[8:9], v[46:47], v[24:25]
	v_mov_b32_e32 v46, v11
	v_mov_b32_e32 v35, v71
	v_mul_f32_e32 v24, v76, v10
	v_add_f32_e32 v10, v8, v9
	v_pk_mul_f32 v[8:9], v[46:47], v[68:69]
	v_mov_b32_e32 v46, v13
	v_mul_f32_e32 v44, v76, v44
	v_mul_f32_e32 v25, v76, v10
	v_add_f32_e32 v10, v8, v9
	v_pk_mul_f32 v[8:9], v[46:47], v[34:35]
	v_mul_f32_e32 v23, v76, v12
	v_add_f32_e32 v8, v8, v9
	v_mul_f32_e32 v29, v76, v10
	v_mul_f32_e32 v45, v76, v8
	v_mul_f32_e32 v50, v50, v50
	v_fmac_f32_e32 v50, v0, v0
	v_mul_f32_e32 v0, v54, v54
	v_mov_b32_e32 v35, v42
	v_mov_b32_e32 v46, v32
	v_mov_b32_e32 v37, v64
	v_mov_b32_e32 v36, v34
	v_fmac_f32_e32 v0, v51, v51
	v_mov_b32_e32 v64, v34
	s_waitcnt lgkmcnt(0)
	v_mov_b32_e32 v39, v74
	v_mov_b32_e32 v38, v34
	v_mul_f32_e32 v4, v44, v4
	v_mul_f32_e32 v5, v22, v5
	v_mul_f32_e32 v6, v27, v6
	v_mul_f32_e32 v7, v24, v7
	v_cvt_pk_bf16_f32 v4, v4, v5
	v_cvt_pk_bf16_f32 v5, v6, v7
	v_mul_f32_e32 v8, v25, v18
	v_mul_f32_e32 v9, v29, v19
	v_mul_f32_e32 v10, v23, v20
	v_mul_f32_e32 v11, v45, v21
	v_mov_b32_e32 v132, v4
	v_mov_b32_e32 v133, v5
	v_cvt_pk_bf16_f32 v4, v8, v9
	v_cvt_pk_bf16_f32 v5, v10, v11
	v_mov_b32_e32 v136, v4
	v_mov_b32_e32 v137, v5
	v_mov_b32_e32 v6, v124
	v_mov_b32_e32 v7, v125
	v_mov_b32_e32 v8, v126
	v_mov_b32_e32 v9, v127
	v_mov_b32_e32 v10, v128
	v_mov_b32_e32 v11, v129
	v_mov_b32_e32 v12, v130
	v_mov_b32_e32 v13, v131
	v_add_f32_e32 v18, v28, v55
	v_mul_f32_e32 v4, v52, v52
	v_add_f32_e32 v18, v18, v26
	v_mul_f32_e32 v5, v53, v53
	v_fmac_f32_e32 v4, v48, v48
	v_add_f32_e32 v18, v18, v56
	v_fmac_f32_e32 v5, v49, v49
	v_add_f32_e32 v4, v18, v4
	v_add_f32_e32 v4, v4, v5
	v_add_f32_e32 v19, v4, v50
	v_mul_f32_e32 v20, v25, v25
	v_pk_mul_f32 v[4:5], v[46:47], v[34:35]
	v_mov_b32_e32 v46, v30
	v_add_f32_e32 v0, v19, v0
	v_fmac_f32_e32 v20, v44, v44
	v_mul_f32_e32 v19, v29, v29
	v_add_f32_e32 v21, v4, v5
	v_pk_mul_f32 v[4:5], v[46:47], v[36:37]
	v_mov_b32_e32 v46, v31
	v_mul_f32_e32 v18, v23, v23
	v_add_f32_e32 v0, v0, v20
	v_fmac_f32_e32 v19, v22, v22
	v_add_f32_e32 v22, v4, v5
	v_pk_mul_f32 v[4:5], v[46:47], v[64:65]
	v_mov_b32_e32 v46, v16
	v_fmac_f32_e32 v18, v27, v27
	v_mov_b32_e32 v35, v43
	v_add_f32_e32 v0, v0, v19
	v_add_f32_e32 v19, v4, v5
	v_pk_mul_f32 v[4:5], v[46:47], v[38:39]
	v_mov_b32_e32 v46, v33
	v_mul_f32_e32 v20, v45, v45
	v_add_f32_e32 v0, v0, v18
	v_mul_f32_e32 v18, v76, v19
	v_add_f32_e32 v19, v4, v5
	v_pk_mul_f32 v[4:5], v[46:47], v[34:35]
	v_mov_b32_e32 v46, v14
	v_fmac_f32_e32 v20, v24, v24
	v_mul_f32_e32 v14, v76, v19
	v_add_f32_e32 v19, v4, v5
	v_pk_mul_f32 v[4:5], v[46:47], v[40:41]
	v_mov_b32_e32 v46, v15
	v_add_f32_e32 v0, v0, v20
	v_add_f32_e32 v20, v4, v5
	v_pk_mul_f32 v[4:5], v[46:47], v[72:73]
	v_mov_b32_e32 v35, v75
	v_mov_b32_e32 v46, v17
	v_mul_f32_e32 v17, v76, v20
	v_add_f32_e32 v20, v4, v5
	v_mul_f32_e32 v16, v76, v22
	v_pk_mul_f32 v[4:5], v[46:47], v[34:35]
	v_mul_f32_e32 v22, v17, v17
	v_mul_f32_e32 v20, v76, v20
	v_add_f32_e32 v4, v4, v5
	v_fmac_f32_e32 v22, v16, v16
	v_mul_f32_e32 v5, v20, v20
	v_mul_f32_e32 v21, v76, v21
	v_mul_f32_e32 v15, v14, v14
	v_mul_f32_e32 v23, v76, v4
	v_add_f32_e32 v0, v0, v22
	v_fmac_f32_e32 v5, v18, v18
	v_mul_f32_e32 v19, v76, v19
	v_fmac_f32_e32 v15, v21, v21
	v_mul_f32_e32 v4, v23, v23
	v_add_f32_e32 v0, v0, v5
	v_fmac_f32_e32 v4, v19, v19
	v_add_f32_e32 v0, v0, v15
	v_add_f32_e32 v0, v0, v4
	ds_bpermute_b32 v4, v149, v0
	v_mul_f32_e32 v5, v16, v6
	v_mul_f32_e32 v6, v18, v7
	v_mul_f32_e32 v7, v21, v8
	v_mul_f32_e32 v8, v19, v9
	v_cvt_pk_bf16_f32 v6, v5, v6
	v_cvt_pk_bf16_f32 v7, v7, v8
	v_mul_f32_e32 v9, v17, v10
	v_mul_f32_e32 v10, v20, v11
	v_mul_f32_e32 v11, v14, v12
	v_mul_f32_e32 v12, v23, v13
	v_mov_b32_e32 v134, v6
	v_mov_b32_e32 v135, v7
	s_nop 1
	v_permlane32_swap_b32_e32 v132, v134
	v_permlane32_swap_b32_e32 v133, v135
	global_store_dwordx4 v[140:141], v[132:135], off offset:32
	v_cvt_pk_bf16_f32 v6, v9, v10
	v_cvt_pk_bf16_f32 v7, v11, v12
	v_mov_b32_e32 v138, v6
	v_mov_b32_e32 v139, v7
	s_nop 1
	v_permlane32_swap_b32_e32 v136, v138
	v_permlane32_swap_b32_e32 v137, v139
	global_store_dwordx4 v[140:141], v[136:139], off offset:96
	s_and_b64 exec, exec, s[0:1]
	s_cbranch_execz .LBB0_929
	v_lshlrev_b64 v[2:3], 5, v[178:179]
	v_lshl_add_u64 v[2:3], s[20:21], 0, v[2:3]
	s_lshl_b32 s10, s47, 2
	v_lshl_add_u64 v[2:3], v[2:3], 0, s[10:11]
	s_waitcnt lgkmcnt(0)
	v_add_f32_e32 v0, v0, v4
	global_store_dword v[2:3], v0, off
	s_branch .LBB0_929
